# v43 + chunk precompute forward substitution: L-row LDS reads issued one row ahead into alternating register banks with counted lgkmcnt
# baseline (speedup 1.0000x reference)
; __device__ __forceinline__ unsigned short f2bf(float f) { return (unsigned short)(pk2(f, 0.f) & 0xffffu); }
; template <int MODE> __device__ void chunk_pass(unsigned char* lds, unsigned char* ws, const float* k_a) {
;     ...
;         if (w == 0) {
;             unsigned char* Tn = SL(3); unsigned char* Tt = SL(2);
;             { const int bi = lane >> 4, cc = lane & 15; float tc[16];
; #pragma unroll
;               for (int t = 0; t < 16; ++t) { float v = (t == cc) ? 1.0f : 0.0f;
; #pragma unroll
;                   for (int jx = 0; jx < t; ++jx) v += Lf[(16 * bi + t) * 64 + 16 * bi + jx] * tc[jx];
;                   tc[t] = v; *(unsigned short*)(Tn + ((16 * bi + t) * LDP + 16 * bi + cc) * 2) = f2bf(v); asm volatile("" ::: "memory"); }
.LBB0_350:
	s_and_b64 vcc, exec, s[24:25]
	v_lshlrev_b32_e32 v75, 2, v74
	s_waitcnt lgkmcnt(0)
	s_barrier
	s_cbranch_vccnz .LBB0_378
	s_nop 1
	v_and_b32_e32 v1, 15, v64
	v_and_b32_e32 v0, -16, v64
	v_readlane_b32 s1, v254, 32
	v_cmp_eq_u32_e32 vcc, 0, v1
	v_or_b32_e32 v92, 15, v64
	v_lshl_add_u32 v19, v0, 2, s1
	s_movk_i32 s1, 0x48
	v_cndmask_b32_e64 v18, 0, 1.0, vcc
	v_mad_u64_u32 v[2:3], s[24:25], v0, s1, v[64:65]
	v_cvt_pk_bf16_f32 v4, v18, s0
	v_lshl_add_u32 v88, v2, 1, 0
	ds_write_b16 v88, v4 offset:27648
	v_lshl_add_u32 v84, v0, 8, v19
	ds_read_b32 v114, v84 offset:256
	ds_read_b64 v[134:135], v84 offset:512
	v_cmp_eq_u32_e32 vcc, 1, v1
	v_add_u32_e32 v12, 0x50c, v84
	v_add_u32_e32 v17, 0x70c, v84
	v_cndmask_b32_e64 v2, 0, 1.0, vcc
	s_waitcnt lgkmcnt(1)
	v_fmac_f32_e32 v2, v18, v114
	v_cvt_pk_bf16_f32 v4, v2, s0
	ds_write_b16 v88, v4 offset:27792
	ds_read_b96 v[114:116], v84 offset:768
	v_cmp_eq_u32_e32 vcc, 2, v1
	v_add_u32_e32 v23, 0x714, v84
	v_add_u32_e32 v25, 0x90c, v84
	v_cndmask_b32_e64 v3, 0, 1.0, vcc
	s_waitcnt lgkmcnt(2)
	v_fmac_f32_e32 v3, v18, v134
	v_fmac_f32_e32 v3, v2, v135
	v_cvt_pk_bf16_f32 v4, v3, s0
	ds_write_b16 v88, v4 offset:27936
	ds_read_b128 v[134:137], v84 offset:1024
	v_cmp_eq_u32_e32 vcc, 3, v1
	v_add_u32_e32 v27, 0x914, v84
	v_add_u32_e32 v28, 0x91c, v84
	v_cndmask_b32_e64 v7, 0, 1.0, vcc
	s_waitcnt lgkmcnt(2)
	v_mov_b32_e32 v8, v115
	v_mov_b32_e32 v9, v116
	v_fmac_f32_e32 v7, v18, v114
	v_pk_mul_f32 v[4:5], v[2:3], v[8:9]
	v_cmp_eq_u32_e32 vcc, 4, v1
	v_add_f32_e32 v4, v7, v4
	v_add_f32_e32 v5, v4, v5
	v_cvt_pk_bf16_f32 v4, v5, s0
	ds_write_b16 v88, v4 offset:28080
	ds_read_b96 v[114:116], v84 offset:1280
	ds_read2_b32 v[118:119], v12 offset1:1
	v_cndmask_b32_e64 v10, 0, 1.0, vcc
	v_mov_b32_e32 v4, v3
	v_cmp_eq_u32_e32 vcc, 5, v1
	v_add_u32_e32 v78, 0xb0c, v84
	s_waitcnt lgkmcnt(3)
	v_fmac_f32_e32 v10, v18, v134
	v_fmac_f32_e32 v10, v2, v135
	v_pk_mul_f32 v[6:7], v[4:5], v[136:137]
	v_cndmask_b32_e64 v11, 0, 1.0, vcc
	v_add_f32_e32 v6, v10, v6
	v_add_f32_e32 v7, v6, v7
	v_cvt_pk_bf16_f32 v6, v7, s0
	ds_write_b16 v88, v6 offset:28224
	ds_read_b128 v[134:137], v84 offset:1536
	ds_read_b64 v[138:139], v84 offset:1552
	v_cmp_eq_u32_e32 vcc, 6, v1
	v_add_u32_e32 v80, 0xb14, v84
	v_add_u32_e32 v81, 0xb1c, v84
	s_waitcnt lgkmcnt(4)
	v_mov_b32_e32 v14, v115
	v_mov_b32_e32 v15, v116
	v_fmac_f32_e32 v11, v18, v114
	v_pk_mul_f32 v[8:9], v[2:3], v[14:15]
	v_cndmask_b32_e64 v16, 0, 1.0, vcc
	v_add_f32_e32 v6, v11, v8
	v_add_f32_e32 v10, v6, v9
	v_mov_b32_e32 v6, v5
	s_waitcnt lgkmcnt(3)
	v_pk_mul_f32 v[8:9], v[6:7], v[118:119]
	v_cmp_eq_u32_e32 vcc, 7, v1
	v_add_f32_e32 v8, v10, v8
	v_add_f32_e32 v9, v8, v9
	v_cvt_pk_bf16_f32 v8, v9, s0
	ds_write_b16 v88, v8 offset:28368
	ds_read_b96 v[114:116], v84 offset:1792
	ds_read2_b32 v[118:119], v17 offset1:1
	ds_read2_b32 v[120:121], v23 offset1:1
	v_cndmask_b32_e64 v22, 0, 1.0, vcc
	v_cmp_eq_u32_e32 vcc, 8, v1
	v_add_u32_e32 v82, 0xb24, v84
	s_waitcnt lgkmcnt(5)
	v_fmac_f32_e32 v16, v18, v134
	v_fmac_f32_e32 v16, v2, v135
	v_pk_mul_f32 v[10:11], v[4:5], v[136:137]
	v_cndmask_b32_e64 v24, 0, 1.0, vcc
	v_add_f32_e32 v8, v16, v10
	v_add_f32_e32 v12, v8, v11
	v_mov_b32_e32 v8, v7
	s_waitcnt lgkmcnt(4)
	v_pk_mul_f32 v[10:11], v[8:9], v[138:139]
	v_cmp_eq_u32_e32 vcc, 9, v1
	v_add_f32_e32 v10, v12, v10
	v_add_f32_e32 v11, v10, v11
	v_cvt_pk_bf16_f32 v10, v11, s0
	ds_write_b16 v88, v10 offset:28512
	ds_read_b128 v[134:137], v84 offset:2048
	ds_read_b128 v[138:141], v84 offset:2064
	v_cndmask_b32_e64 v26, 0, 1.0, vcc
	v_cmp_eq_u32_e32 vcc, 10, v1
	v_add_u32_e32 v86, 0xd0c, v84
	s_waitcnt lgkmcnt(5)
	v_mov_b32_e32 v20, v115
	v_mov_b32_e32 v21, v116
	v_fmac_f32_e32 v22, v18, v114
	v_pk_mul_f32 v[12:13], v[2:3], v[20:21]
	v_cndmask_b32_e64 v30, 0, 1.0, vcc
	v_add_f32_e32 v10, v22, v12
	v_add_f32_e32 v10, v10, v13
	s_waitcnt lgkmcnt(4)
	v_pk_mul_f32 v[14:15], v[6:7], v[118:119]
	v_cmp_eq_u32_e32 vcc, 11, v1
	v_add_f32_e32 v10, v10, v14
	v_add_f32_e32 v14, v10, v15
	v_mov_b32_e32 v10, v9
	s_waitcnt lgkmcnt(3)
	v_pk_mul_f32 v[12:13], v[10:11], v[120:121]
	v_cndmask_b32_e64 v31, 0, 1.0, vcc
	v_add_f32_e32 v12, v14, v12
	v_add_f32_e32 v13, v12, v13
	v_cvt_pk_bf16_f32 v12, v13, s0
	ds_write_b16 v88, v12 offset:28656
	ds_read_b96 v[114:116], v84 offset:2304
	ds_read2_b32 v[118:119], v25 offset1:1
	ds_read2_b32 v[120:121], v27 offset1:1
	ds_read2_b32 v[122:123], v28 offset1:1
	v_cmp_eq_u32_e32 vcc, 12, v1
	v_add_u32_e32 v87, 0xd14, v84
	v_add_u32_e32 v89, 0xd1c, v84
	s_waitcnt lgkmcnt(6)
	v_fmac_f32_e32 v24, v18, v134
	v_fmac_f32_e32 v24, v2, v135
	v_pk_mul_f32 v[14:15], v[4:5], v[136:137]
	v_cndmask_b32_e64 v83, 0, 1.0, vcc
	v_add_f32_e32 v12, v24, v14
	v_add_f32_e32 v12, v12, v15
	s_waitcnt lgkmcnt(5)
	v_pk_mul_f32 v[14:15], v[8:9], v[138:139]
	v_cmp_eq_u32_e32 vcc, 13, v1
	v_add_f32_e32 v12, v12, v14
	v_add_f32_e32 v16, v12, v15
	v_mov_b32_e32 v12, v11
	v_pk_mul_f32 v[14:15], v[12:13], v[140:141]
	v_cndmask_b32_e64 v85, 0, 1.0, vcc
	v_add_f32_e32 v14, v16, v14
	v_add_f32_e32 v15, v14, v15
	v_cvt_pk_bf16_f32 v14, v15, s0
	ds_write_b16 v88, v14 offset:28800
	ds_read_b128 v[134:137], v84 offset:2560
	ds_read_b128 v[138:141], v84 offset:2576
	ds_read_b64 v[142:143], v84 offset:2592
	v_add_u32_e32 v90, 0xd2c, v84
	v_cmp_eq_u32_e32 vcc, 14, v1
	v_lshl_add_u32 v19, v92, 8, v19
	s_waitcnt lgkmcnt(7)
	v_mov_b32_e32 v24, v115
	v_mov_b32_e32 v25, v116
	v_fmac_f32_e32 v26, v18, v114
	v_pk_mul_f32 v[20:21], v[2:3], v[24:25]
	s_waitcnt lgkmcnt(6)
	v_pk_mul_f32 v[16:17], v[6:7], v[118:119]
	v_add_f32_e32 v14, v26, v20
	v_add_f32_e32 v14, v14, v21
	v_add_f32_e32 v14, v14, v16
	v_add_f32_e32 v14, v14, v17
	v_cndmask_b32_e64 v91, 0, 1.0, vcc
	s_waitcnt lgkmcnt(5)
; __device__ __forceinline__ unsigned short f2bf(float f) { return (unsigned short)(pk2(f, 0.f) & 0xffffu); }
; template <int MODE> __device__ void chunk_pass(unsigned char* lds, unsigned char* ws, const float* k_a) {
;     ...
;             { const int bi = lane >> 4, cc = lane & 15; float tc[16];
; #pragma unroll
;               for (int t = 0; t < 16; ++t) { float v = (t == cc) ? 1.0f : 0.0f;
; #pragma unroll
;                   for (int jx = 0; jx < t; ++jx) v += Lf[(16 * bi + t) * 64 + 16 * bi + jx] * tc[jx];
;                   tc[t] = v; *(unsigned short*)(Tn + ((16 * bi + t) * LDP + 16 * bi + cc) * 2) = f2bf(v); asm volatile("" ::: "memory"); }
	v_pk_mul_f32 v[20:21], v[10:11], v[120:121]
	v_cmp_eq_u32_e32 vcc, 15, v1
	v_add_f32_e32 v14, v14, v20
	v_add_f32_e32 v20, v14, v21
	v_mov_b32_e32 v14, v13
	s_waitcnt lgkmcnt(4)
	v_pk_mul_f32 v[16:17], v[14:15], v[122:123]
	s_movk_i32 s21, 0x48
	v_add_f32_e32 v16, v20, v16
	v_add_f32_e32 v17, v16, v17
	v_cvt_pk_bf16_f32 v16, v17, s0
	ds_write_b16 v88, v16 offset:28944
	ds_read_b96 v[114:116], v84 offset:2816
	ds_read2_b32 v[118:119], v78 offset1:1
	ds_read2_b32 v[120:121], v80 offset1:1
	ds_read2_b32 v[122:123], v81 offset1:1
	ds_read2_b32 v[124:125], v82 offset1:1
	s_waitcnt lgkmcnt(8)
	v_fmac_f32_e32 v30, v18, v134
	v_fmac_f32_e32 v30, v2, v135
	v_pk_mul_f32 v[20:21], v[4:5], v[136:137]
	s_nop 0
	v_add_f32_e32 v16, v30, v20
	v_add_f32_e32 v16, v16, v21
	s_waitcnt lgkmcnt(7)
	v_pk_mul_f32 v[20:21], v[8:9], v[138:139]
	s_nop 0
	v_add_f32_e32 v16, v16, v20
	v_add_f32_e32 v16, v16, v21
	v_pk_mul_f32 v[20:21], v[12:13], v[140:141]
	s_nop 0
	v_add_f32_e32 v16, v16, v20
	v_add_f32_e32 v22, v16, v21
	v_mov_b32_e32 v16, v15
	s_waitcnt lgkmcnt(6)
	v_pk_mul_f32 v[20:21], v[16:17], v[142:143]
	s_nop 0
	v_add_f32_e32 v20, v22, v20
	v_add_f32_e32 v79, v20, v21
	v_cvt_pk_bf16_f32 v20, v79, s0
	ds_write_b16 v88, v20 offset:29088
	ds_read_b128 v[134:137], v84 offset:3072
	ds_read_b128 v[138:141], v84 offset:3088
	ds_read_b128 v[142:145], v84 offset:3104
	s_waitcnt lgkmcnt(8)
	v_mov_b32_e32 v26, v115
	v_mov_b32_e32 v27, v116
	v_fmac_f32_e32 v31, v18, v114
	v_pk_mul_f32 v[20:21], v[2:3], v[26:27]
	v_add_f32_e32 v20, v31, v20
	v_add_f32_e32 v26, v20, v21
	s_waitcnt lgkmcnt(7)
	v_pk_mul_f32 v[20:21], v[6:7], v[118:119]
	v_mov_b32_e32 v78, v17
	v_add_f32_e32 v20, v26, v20
	v_add_f32_e32 v26, v20, v21
	s_waitcnt lgkmcnt(6)
	v_pk_mul_f32 v[22:23], v[10:11], v[120:121]
	v_mov_b32_e32 v80, v79
	v_add_f32_e32 v22, v26, v22
	v_add_f32_e32 v22, v22, v23
	s_waitcnt lgkmcnt(5)
	v_pk_mul_f32 v[20:21], v[14:15], v[122:123]
	v_add_u32_e32 v82, 0xd24, v84
	v_add_f32_e32 v20, v22, v20
	v_add_f32_e32 v22, v20, v21
	s_waitcnt lgkmcnt(4)
	v_pk_mul_f32 v[20:21], v[78:79], v[124:125]
	s_nop 0
	v_add_f32_e32 v20, v22, v20
	v_add_f32_e32 v81, v20, v21
	v_cvt_pk_bf16_f32 v20, v81, s0
	ds_write_b16 v88, v20 offset:29232
	ds_read_b96 v[114:116], v84 offset:3328
	ds_read2_b32 v[118:119], v86 offset1:1
	ds_read2_b32 v[120:121], v87 offset1:1
	ds_read2_b32 v[122:123], v89 offset1:1
	ds_read2_b32 v[124:125], v82 offset1:1
	ds_read2_b32 v[126:127], v90 offset1:1
	s_waitcnt lgkmcnt(9)
	v_fmac_f32_e32 v83, v18, v134
	v_fmac_f32_e32 v83, v2, v135
	v_pk_mul_f32 v[20:21], v[4:5], v[136:137]
	s_nop 0
	v_add_f32_e32 v20, v83, v20
	v_add_f32_e32 v22, v20, v21
	s_waitcnt lgkmcnt(8)
	v_pk_mul_f32 v[20:21], v[8:9], v[138:139]
	s_nop 0
	v_add_f32_e32 v20, v22, v20
	v_add_f32_e32 v22, v20, v21
	v_pk_mul_f32 v[20:21], v[12:13], v[140:141]
	s_nop 0
	v_add_f32_e32 v20, v22, v20
	v_add_f32_e32 v22, v20, v21
	s_waitcnt lgkmcnt(7)
	v_pk_mul_f32 v[20:21], v[16:17], v[142:143]
	s_nop 0
	v_add_f32_e32 v20, v22, v20
	v_add_f32_e32 v22, v20, v21
	v_pk_mul_f32 v[20:21], v[80:81], v[144:145]
	s_nop 0
	v_add_f32_e32 v20, v22, v20
	v_add_f32_e32 v83, v20, v21
	v_cvt_pk_bf16_f32 v20, v83, s0
	ds_write_b16 v88, v20 offset:29376
	ds_read_b128 v[134:137], v84 offset:3584
	ds_read_b128 v[138:141], v84 offset:3600
	ds_read_b128 v[142:145], v84 offset:3616
	ds_read_b64 v[146:147], v84 offset:3632
	s_waitcnt lgkmcnt(10)
	v_mov_b32_e32 v26, v115
	v_mov_b32_e32 v27, v116
	v_fmac_f32_e32 v85, v18, v114
	v_pk_mul_f32 v[20:21], v[2:3], v[26:27]
	s_nop 0
	v_add_f32_e32 v20, v85, v20
	v_add_f32_e32 v22, v20, v21
	s_waitcnt lgkmcnt(9)
	v_pk_mul_f32 v[20:21], v[6:7], v[118:119]
	s_nop 0
	v_add_f32_e32 v20, v22, v20
	v_add_f32_e32 v28, v20, v21
	v_mov_b32_e32 v82, v81
	s_waitcnt lgkmcnt(8)
	v_pk_mul_f32 v[22:23], v[10:11], v[120:121]
	s_nop 0
	v_add_f32_e32 v22, v28, v22
	v_add_f32_e32 v22, v22, v23
	s_waitcnt lgkmcnt(7)
	v_pk_mul_f32 v[20:21], v[14:15], v[122:123]
	s_nop 0
	v_add_f32_e32 v20, v22, v20
	v_add_f32_e32 v22, v20, v21
	s_waitcnt lgkmcnt(6)
	v_pk_mul_f32 v[20:21], v[78:79], v[124:125]
	s_nop 0
	v_add_f32_e32 v20, v22, v20
	v_add_f32_e32 v22, v20, v21
	s_waitcnt lgkmcnt(5)
	v_pk_mul_f32 v[20:21], v[82:83], v[126:127]
	s_nop 0
	v_add_f32_e32 v20, v22, v20
	v_add_f32_e32 v85, v20, v21
	v_cvt_pk_bf16_f32 v20, v85, s0
	ds_write_b16 v88, v20 offset:29520
	v_mov_b32_e32 v84, v83
	s_waitcnt lgkmcnt(4)
	v_fmac_f32_e32 v91, v18, v134
	v_fmac_f32_e32 v91, v2, v135
	v_pk_mul_f32 v[20:21], v[4:5], v[136:137]
	s_nop 0
	v_add_f32_e32 v4, v91, v20
	v_add_f32_e32 v4, v4, v21
	s_waitcnt lgkmcnt(3)
	v_pk_mul_f32 v[20:21], v[8:9], v[138:139]
	s_nop 0
	v_add_f32_e32 v4, v4, v20
	v_add_f32_e32 v4, v4, v21
	v_pk_mul_f32 v[20:21], v[12:13], v[140:141]
	s_nop 0
	v_add_f32_e32 v4, v4, v20
	v_add_f32_e32 v4, v4, v21
	s_waitcnt lgkmcnt(2)
; __device__ __forceinline__ unsigned pk2(float lo, float hi) { f32x2n v = {lo, hi}; return __builtin_bit_cast(unsigned, __builtin_convertvector(v, bf16x2n)); }
; __device__ __forceinline__ unsigned short f2bf(float f) { return (unsigned short)(pk2(f, 0.f) & 0xffffu); }
; template <int MODE> __device__ void chunk_pass(unsigned char* lds, unsigned char* ws, const float* k_a) {
;     ...
;             { const int bi = lane >> 4, cc = lane & 15; float tc[16];
; #pragma unroll
;               for (int t = 0; t < 16; ++t) { float v = (t == cc) ? 1.0f : 0.0f;
; #pragma unroll
;                   for (int jx = 0; jx < t; ++jx) v += Lf[(16 * bi + t) * 64 + 16 * bi + jx] * tc[jx];
;                   tc[t] = v; *(unsigned short*)(Tn + ((16 * bi + t) * LDP + 16 * bi + cc) * 2) = f2bf(v); asm volatile("" ::: "memory"); }
;               *(u32x4*)(Tt + ((16 * bi + cc) * LDP + 16 * bi) * 2) = pack8(tc); *(u32x4*)(Tt + ((16 * bi + cc) * LDP + 16 * bi + 8) * 2) = pack8(tc + 8); }
;             asm volatile("s_waitcnt lgkmcnt(0)" ::: "memory");
;             const int pr = l32 >> 4, i16 = l32 & 15;
;             {
;               const bf16x8 a1 = *(const bf16x8*)(SL(0) + ((32 * pr + 16 + i16) * LDP + 32 * pr + 8 * hi) * 2);
;               const bf16x8 b1 = *(const bf16x8*)(Tt + ((32 * pr + i16) * LDP + 32 * pr + 8 * hi) * 2);
;               f32x16 m1 = __builtin_amdgcn_mfma_f32_32x32x16_bf16(a1, b1, zero16(), 0, 0, 0);
; #pragma unroll
;               for (int g = 0; g < 4; ++g) { const int row = 8 * g + 4 * hi; u32x2 wv; wv.x = pk2(m1[4 * g], m1[4 * g + 1]); wv.y = pk2(m1[4 * g + 2], m1[4 * g + 3]); *(u32x2*)(SC + (l32 * 40 + row) * 2) = wv; }
;               asm volatile("s_waitcnt lgkmcnt(0)" ::: "memory");
;               const bf16x8 a2 = *(const bf16x8*)(Tn + ((32 * pr + 16 + i16) * LDP + 32 * pr + 16 + 8 * hi) * 2);
;               const bf16x8 b2 = *(const bf16x8*)(SC + (l32 * 40 + 16 * pr + 8 * hi) * 2);
;               f32x16 t1 = __builtin_amdgcn_mfma_f32_32x32x16_bf16(a2, b2, zero16(), 0, 0, 0);
; #pragma unroll
;               for (int r = 0; r < 16; ++r) { const int row = crow(r, hi); if ((row >> 4) == pr) { const unsigned short hv = f2bf(t1[r]);
;                   *(unsigned short*)(Tn + ((32 * pr + 16 + (row & 15)) * LDP + 32 * pr + i16) * 2) = hv; *(unsigned short*)(Tt + ((32 * pr + i16) * LDP + 32 * pr + 16 + (row & 15)) * 2) = hv; } }
	v_pk_mul_f32 v[20:21], v[16:17], v[142:143]
	s_nop 0
	v_add_f32_e32 v4, v4, v20
	v_add_f32_e32 v4, v4, v21
	v_pk_mul_f32 v[20:21], v[80:81], v[144:145]
	s_nop 0
	v_add_f32_e32 v4, v4, v20
	v_add_f32_e32 v4, v4, v21
	s_waitcnt lgkmcnt(1)
	v_pk_mul_f32 v[20:21], v[84:85], v[146:147]
	s_nop 0
	v_add_f32_e32 v4, v4, v20
	v_add_f32_e32 v23, v4, v21
	v_cvt_pk_bf16_f32 v4, v23, s0
	ds_write_b16 v88, v4 offset:29664
	ds_read_b96 v[20:22], v19
	ds_read2_b32 v[24:25], v19 offset0:3 offset1:4
	v_cndmask_b32_e64 v4, 0, 1.0, vcc
	s_waitcnt lgkmcnt(1)
	v_fmac_f32_e32 v4, v18, v20
	v_fmac_f32_e32 v4, v2, v21
	s_waitcnt lgkmcnt(0)
	v_pk_mul_f32 v[20:21], v[6:7], v[24:25]
	ds_read2_b32 v[24:25], v19 offset0:5 offset1:6
	v_fmac_f32_e32 v4, v3, v22
	v_add_f32_e32 v4, v4, v20
	v_add_f32_e32 v4, v4, v21
	ds_read2_b32 v[20:21], v19 offset0:7 offset1:8
	ds_read2_b32 v[26:27], v19 offset0:9 offset1:10
	ds_read2_b32 v[28:29], v19 offset0:11 offset1:12
	s_waitcnt lgkmcnt(3)
	v_pk_mul_f32 v[24:25], v[10:11], v[24:25]
	v_mov_b32_e32 v22, v85
	v_add_f32_e32 v4, v4, v24
	v_add_f32_e32 v4, v4, v25
	s_waitcnt lgkmcnt(2)
	v_pk_mul_f32 v[20:21], v[14:15], v[20:21]
	s_waitcnt lgkmcnt(0)
	v_pk_mul_f32 v[24:25], v[82:83], v[28:29]
	v_add_f32_e32 v4, v4, v20
	v_add_f32_e32 v4, v4, v21
	v_pk_mul_f32 v[20:21], v[78:79], v[26:27]
	v_cvt_pk_bf16_f32 v2, v18, v2
	v_add_f32_e32 v4, v4, v20
	v_add_f32_e32 v4, v4, v21
	ds_read2_b32 v[20:21], v19 offset0:13 offset1:14
	v_add_f32_e32 v4, v4, v24
	v_add_f32_e32 v4, v4, v25
	v_cvt_pk_bf16_f32 v3, v3, v5
	v_cvt_pk_bf16_f32 v5, v11, v13
	s_waitcnt lgkmcnt(0)
	v_pk_mul_f32 v[20:21], v[22:23], v[20:21]
	v_lshrrev_b32_e32 v25, 4, v72
	v_add_f32_e32 v4, v4, v20
	v_add_f32_e32 v8, v4, v21
	v_mad_u64_u32 v[20:21], s[24:25], v92, s1, v[64:65]
	v_cvt_pk_bf16_f32 v4, v8, s0
	v_lshl_add_u32 v6, v20, 1, 0
	ds_write_b16 v6, v4 offset:27648
	v_cvt_pk_bf16_f32 v4, v7, v9
	v_mad_u64_u32 v[6:7], s[24:25], v64, s1, v[0:1]
	v_lshl_add_u32 v0, v6, 1, 0
	ds_write_b128 v0, v[2:5] offset:18432
	v_cvt_pk_bf16_f32 v2, v15, v17
	v_cvt_pk_bf16_f32 v3, v79, v81
	v_cvt_pk_bf16_f32 v4, v83, v85
	v_cvt_pk_bf16_f32 v5, v23, v8
	ds_write_b128 v0, v[2:5] offset:18448
	v_lshlrev_b32_e32 v0, 5, v25
	v_or_b32_e32 v23, 16, v0
	v_or_b32_e32 v2, v23, v1
	v_mul_u32_u24_e32 v2, 0x48, v2
	v_lshlrev_b32_e32 v22, 3, v74
	v_add3_u32 v2, v0, v22, v2
	s_waitcnt lgkmcnt(0)
	v_lshl_add_u32 v16, v2, 1, 0
	ds_read_b128 v[2:5], v16
	v_or_b32_e32 v24, v0, v1
	v_mad_u32_u24 v17, v24, s1, v0
	v_add_u32_e32 v0, v17, v22
	v_lshl_add_u32 v0, v0, 1, 0
	ds_read_b128 v[6:9], v0 offset:18432
	s_waitcnt lgkmcnt(0)
	v_mfma_f32_32x32x16_bf16 v[0:15], v[2:5], v[6:9], 0
	v_readlane_b32 s24, v254, 35
	s_movk_i32 s1, 0x50
	v_readlane_b32 s25, v254, 36
	v_add_u32_e32 v20, s24, v22
	v_add_u32_e32 v26, 16, v17
	v_add_u32_e32 v21, s25, v22
	v_readlane_b32 s25, v254, 37
	s_nop 4
	v_cvt_pk_bf16_f32 v0, v0, v1
	v_cvt_pk_bf16_f32 v1, v2, v3
	v_mad_u32_u24 v2, v72, s1, v20
	ds_write_b64 v2, v[0:1]
	v_cvt_pk_bf16_f32 v0, v4, v5
	v_cvt_pk_bf16_f32 v1, v6, v7
	v_mad_u32_u24 v2, v72, s1, v21
	v_add_u32_e32 v19, s25, v22
	v_readlane_b32 s25, v254, 38
	ds_write_b64 v2, v[0:1]
	v_cvt_pk_bf16_f32 v0, v8, v9
	v_cvt_pk_bf16_f32 v1, v10, v11
	v_mad_u32_u24 v2, v72, s1, v19
	v_add_u32_e32 v18, s25, v22
	ds_write_b64 v2, v[0:1]
	v_cvt_pk_bf16_f32 v0, v12, v13
	v_cvt_pk_bf16_f32 v1, v14, v15
	v_mad_u32_u24 v2, v72, s1, v18
	ds_write_b64 v2, v[0:1]
	s_waitcnt lgkmcnt(0)
	ds_read_b128 v[0:3], v16 offset:27680
	v_and_b32_e32 v4, 16, v64
	v_mad_u32_u24 v16, v72, 40, v22
	v_add_u32_e32 v4, v16, v4
	v_lshl_add_u32 v4, v4, 1, s24
	ds_read_b128 v[4:7], v4
	v_ashrrev_i32_e32 v17, 7, v64
	s_waitcnt lgkmcnt(0)
	v_mfma_f32_32x32x16_bf16 v[0:15], v[0:3], v[4:7], 0
	v_cmp_eq_u32_e32 vcc, v17, v25
	v_and_b32_e32 v17, 12, v75
	v_or_b32_e32 v28, v23, v17
	v_add_u32_e32 v27, v26, v17
	s_and_saveexec_b64 s[24:25], vcc
	s_cbranch_execz .LBB0_353
	s_movk_i32 s1, 0x48
	v_mad_u32_u24 v29, v28, s1, v24
	s_nop 3
	v_cvt_pk_bf16_f32 v0, v0, s0
	v_lshl_add_u32 v29, v29, 1, 0
	ds_write_b16 v29, v0 offset:27648
	v_lshl_add_u32 v29, v27, 1, 0
	ds_write_b16 v29, v0 offset:18432
	v_cvt_pk_bf16_f32 v0, v1, s0
	v_or_b32_e32 v1, 1, v17
	v_or_b32_e32 v29, v1, v23
	v_mad_u32_u24 v29, v29, s1, v24
	v_add_u32_e32 v1, v26, v1
	v_lshl_add_u32 v29, v29, 1, 0
	v_lshl_add_u32 v1, v1, 1, 0
	ds_write_b16 v29, v0 offset:27648
	ds_write_b16 v1, v0 offset:18432
	v_or_b32_e32 v1, 2, v17
	v_cvt_pk_bf16_f32 v0, v2, s0
	v_or_b32_e32 v2, v1, v23
	v_mad_u32_u24 v2, v2, s1, v24
	v_add_u32_e32 v1, v26, v1
	v_lshl_add_u32 v2, v2, 1, 0
	v_lshl_add_u32 v1, v1, 1, 0
	ds_write_b16 v2, v0 offset:27648
	ds_write_b16 v1, v0 offset:18432
	v_or_b32_e32 v1, 3, v17
	v_or_b32_e32 v2, v1, v23
	v_mad_u32_u24 v2, v2, s1, v24
	v_add_u32_e32 v1, v26, v1
	v_cvt_pk_bf16_f32 v0, v3, s0
	v_lshl_add_u32 v2, v2, 1, 0
	v_lshl_add_u32 v1, v1, 1, 0
	ds_write_b16 v2, v0 offset:27648
	ds_write_b16 v1, v0 offset:18432
